# adds attention epilogue output stores widened 8B->16B per lane via v_permlane32_swap_b32 across the two half-waves (16->8 stores per item), on top of the widened tile stores/loads
# speedup vs baseline: 1.0490x; 1.0064x over previous
.LBB0_243:
	s_or_b64 exec, exec, s[8:9]
	s_waitcnt lgkmcnt(0)
	s_barrier
	s_and_saveexec_b64 s[8:9], s[52:53]
	s_cbranch_execz .LBB0_214
	v_rcp_f32_e32 v132, v132
	ds_read2st64_b32 v[160:161], v199 offset1:1
	ds_read2st64_b32 v[162:163], v199 offset0:2 offset1:3
	ds_read2st64_b32 v[164:165], v199 offset0:4 offset1:5
	ds_read2st64_b32 v[166:167], v199 offset0:6 offset1:7
	ds_read2st64_b32 v[168:169], v199 offset0:8 offset1:9
	ds_read2st64_b32 v[170:171], v199 offset0:10 offset1:11
	ds_read2st64_b32 v[172:173], v199 offset0:12 offset1:13
	ds_read2st64_b32 v[174:175], v199 offset0:14 offset1:15
	ds_read2st64_b32 v[176:177], v199 offset0:16 offset1:17
	ds_read2st64_b32 v[178:179], v199 offset0:18 offset1:19
	ds_read2st64_b32 v[180:181], v199 offset0:20 offset1:21
	ds_read2st64_b32 v[182:183], v199 offset0:22 offset1:23
	ds_read2st64_b32 v[184:185], v199 offset0:24 offset1:25
	ds_read2st64_b32 v[186:187], v199 offset0:26 offset1:27
	ds_read2st64_b32 v[188:189], v199 offset0:28 offset1:29
	ds_read2st64_b32 v[212:213], v199 offset0:30 offset1:31
	ds_read2st64_b32 v[214:215], v199 offset0:32 offset1:33
	ds_read2st64_b32 v[216:217], v199 offset0:34 offset1:35
	ds_read2st64_b32 v[218:219], v199 offset0:36 offset1:37
	ds_read2st64_b32 v[220:221], v199 offset0:38 offset1:39
	ds_read2st64_b32 v[222:223], v199 offset0:40 offset1:41
	ds_read2st64_b32 v[224:225], v199 offset0:42 offset1:43
	ds_read2st64_b32 v[226:227], v199 offset0:44 offset1:45
	ds_read2st64_b32 v[228:229], v199 offset0:46 offset1:47
	ds_read2st64_b32 v[230:231], v199 offset0:56 offset1:57
	ds_read2st64_b32 v[232:233], v199 offset0:58 offset1:59
	ds_read2st64_b32 v[234:235], v199 offset0:60 offset1:61
	ds_read2st64_b32 v[236:237], v199 offset0:62 offset1:63
	ds_read2st64_b32 v[238:239], v199 offset0:48 offset1:49
	ds_read2st64_b32 v[240:241], v199 offset0:50 offset1:51
	ds_read2st64_b32 v[242:243], v199 offset0:52 offset1:53
	ds_read2st64_b32 v[244:245], v199 offset0:54 offset1:55
	v_mov_b32_e32 v153, v133
	s_waitcnt lgkmcnt(14)
	v_pk_fma_f32 v[50:51], v[50:51], v[132:133], v[160:161] op_sel_hi:[1,0,1] neg_lo:[0,0,1] neg_hi:[0,0,1]
	v_pk_fma_f32 v[52:53], v[52:53], v[132:133], v[162:163] op_sel_hi:[1,0,1] neg_lo:[0,0,1] neg_hi:[0,0,1]
	v_pk_mul_f32 v[160:161], v[50:51], v[50:51]
	s_waitcnt lgkmcnt(5)
	v_pk_fma_f32 v[14:15], v[14:15], v[132:133], v[234:235] op_sel_hi:[1,0,1] neg_lo:[0,0,1] neg_hi:[0,0,1]
	s_waitcnt lgkmcnt(4)
	v_pk_fma_f32 v[16:17], v[16:17], v[132:133], v[236:237] op_sel_hi:[1,0,1] neg_lo:[0,0,1] neg_hi:[0,0,1]
	v_pk_mul_f32 v[162:163], v[52:53], v[52:53]
	v_pk_fma_f32 v[56:57], v[56:57], v[132:133], v[166:167] op_sel_hi:[1,0,1] neg_lo:[0,0,1] neg_hi:[0,0,1]
	v_pk_fma_f32 v[54:55], v[54:55], v[132:133], v[164:165] op_sel_hi:[1,0,1] neg_lo:[0,0,1] neg_hi:[0,0,1]
	v_pk_fma_f32 v[60:61], v[60:61], v[132:133], v[170:171] op_sel_hi:[1,0,1] neg_lo:[0,0,1] neg_hi:[0,0,1]
	v_pk_fma_f32 v[58:59], v[58:59], v[132:133], v[168:169] op_sel_hi:[1,0,1] neg_lo:[0,0,1] neg_hi:[0,0,1]
	v_pk_fma_f32 v[64:65], v[64:65], v[132:133], v[174:175] op_sel_hi:[1,0,1] neg_lo:[0,0,1] neg_hi:[0,0,1]
	v_pk_fma_f32 v[62:63], v[62:63], v[132:133], v[172:173] op_sel_hi:[1,0,1] neg_lo:[0,0,1] neg_hi:[0,0,1]
	v_pk_fma_f32 v[36:37], v[36:37], v[132:133], v[178:179] op_sel_hi:[1,0,1] neg_lo:[0,0,1] neg_hi:[0,0,1]
	v_pk_fma_f32 v[34:35], v[34:35], v[132:133], v[176:177] op_sel_hi:[1,0,1] neg_lo:[0,0,1] neg_hi:[0,0,1]
	v_pk_fma_f32 v[40:41], v[40:41], v[132:133], v[182:183] op_sel_hi:[1,0,1] neg_lo:[0,0,1] neg_hi:[0,0,1]
	v_pk_fma_f32 v[38:39], v[38:39], v[132:133], v[180:181] op_sel_hi:[1,0,1] neg_lo:[0,0,1] neg_hi:[0,0,1]
	v_pk_fma_f32 v[44:45], v[44:45], v[132:133], v[186:187] op_sel_hi:[1,0,1] neg_lo:[0,0,1] neg_hi:[0,0,1]
	v_pk_fma_f32 v[42:43], v[42:43], v[132:133], v[184:185] op_sel_hi:[1,0,1] neg_lo:[0,0,1] neg_hi:[0,0,1]
	v_pk_fma_f32 v[48:49], v[48:49], v[132:133], v[212:213] op_sel_hi:[1,0,1] neg_lo:[0,0,1] neg_hi:[0,0,1]
	v_pk_fma_f32 v[46:47], v[46:47], v[132:133], v[188:189] op_sel_hi:[1,0,1] neg_lo:[0,0,1] neg_hi:[0,0,1]
	v_pk_fma_f32 v[20:21], v[20:21], v[132:133], v[216:217] op_sel_hi:[1,0,1] neg_lo:[0,0,1] neg_hi:[0,0,1]
	v_pk_fma_f32 v[18:19], v[18:19], v[132:133], v[214:215] op_sel_hi:[1,0,1] neg_lo:[0,0,1] neg_hi:[0,0,1]
	v_pk_fma_f32 v[24:25], v[24:25], v[132:133], v[220:221] op_sel_hi:[1,0,1] neg_lo:[0,0,1] neg_hi:[0,0,1]
	v_pk_fma_f32 v[22:23], v[22:23], v[132:133], v[218:219] op_sel_hi:[1,0,1] neg_lo:[0,0,1] neg_hi:[0,0,1]
	v_pk_fma_f32 v[28:29], v[28:29], v[132:133], v[224:225] op_sel_hi:[1,0,1] neg_lo:[0,0,1] neg_hi:[0,0,1]
	v_pk_fma_f32 v[26:27], v[26:27], v[132:133], v[222:223] op_sel_hi:[1,0,1] neg_lo:[0,0,1] neg_hi:[0,0,1]
	v_pk_fma_f32 v[32:33], v[32:33], v[132:133], v[228:229] op_sel_hi:[1,0,1] neg_lo:[0,0,1] neg_hi:[0,0,1]
	v_pk_fma_f32 v[30:31], v[30:31], v[132:133], v[226:227] op_sel_hi:[1,0,1] neg_lo:[0,0,1] neg_hi:[0,0,1]
	s_waitcnt lgkmcnt(2)
	v_pk_fma_f32 v[4:5], v[4:5], v[132:133], v[240:241] op_sel_hi:[1,0,1] neg_lo:[0,0,1] neg_hi:[0,0,1]
	v_pk_fma_f32 v[2:3], v[2:3], v[132:133], v[238:239] op_sel_hi:[1,0,1] neg_lo:[0,0,1] neg_hi:[0,0,1]
	s_waitcnt lgkmcnt(0)
	v_pk_fma_f32 v[8:9], v[8:9], v[132:133], v[244:245] op_sel_hi:[1,0,1] neg_lo:[0,0,1] neg_hi:[0,0,1]
	v_pk_fma_f32 v[6:7], v[6:7], v[132:133], v[242:243] op_sel_hi:[1,0,1] neg_lo:[0,0,1] neg_hi:[0,0,1]
	v_pk_fma_f32 v[12:13], v[12:13], v[132:133], v[232:233] op_sel_hi:[1,0,1] neg_lo:[0,0,1] neg_hi:[0,0,1]
	v_pk_fma_f32 v[10:11], v[10:11], v[132:133], v[230:231] op_sel_hi:[1,0,1] neg_lo:[0,0,1] neg_hi:[0,0,1]
	v_add_f32_e32 v132, v160, v161
	v_add_f32_e32 v132, v132, v162
	v_pk_mul_f32 v[164:165], v[54:55], v[54:55]
	v_add_f32_e32 v132, v132, v163
	v_add_f32_e32 v132, v132, v164
	v_pk_mul_f32 v[166:167], v[56:57], v[56:57]
	v_add_f32_e32 v132, v132, v165
	v_add_f32_e32 v132, v132, v166
	v_pk_mul_f32 v[168:169], v[58:59], v[58:59]
	v_add_f32_e32 v132, v132, v167
	v_add_f32_e32 v132, v132, v168
	v_pk_mul_f32 v[170:171], v[60:61], v[60:61]
	v_add_f32_e32 v132, v132, v169
	v_add_f32_e32 v132, v132, v170
	v_pk_mul_f32 v[172:173], v[62:63], v[62:63]
	v_add_f32_e32 v132, v132, v171
	v_add_f32_e32 v132, v132, v172
	v_pk_mul_f32 v[174:175], v[64:65], v[64:65]
	v_add_f32_e32 v132, v132, v173
	v_add_f32_e32 v132, v132, v174
	v_pk_mul_f32 v[176:177], v[34:35], v[34:35]
	v_add_f32_e32 v132, v132, v175
	v_add_f32_e32 v132, v132, v176
	v_pk_mul_f32 v[178:179], v[36:37], v[36:37]
	v_add_f32_e32 v132, v132, v177
	v_add_f32_e32 v132, v132, v178
	v_pk_mul_f32 v[180:181], v[38:39], v[38:39]
	v_add_f32_e32 v132, v132, v179
	v_add_f32_e32 v132, v132, v180
	v_pk_mul_f32 v[182:183], v[40:41], v[40:41]
	v_add_f32_e32 v132, v132, v181
	v_add_f32_e32 v132, v132, v182
	v_pk_mul_f32 v[184:185], v[42:43], v[42:43]
	v_add_f32_e32 v132, v132, v183
	v_add_f32_e32 v132, v132, v184
	v_pk_mul_f32 v[186:187], v[44:45], v[44:45]
	v_add_f32_e32 v132, v132, v185
	v_add_f32_e32 v132, v132, v186
	v_pk_mul_f32 v[188:189], v[46:47], v[46:47]
	v_add_f32_e32 v132, v132, v187
	v_add_f32_e32 v132, v132, v188
	v_pk_mul_f32 v[212:213], v[48:49], v[48:49]
	v_add_f32_e32 v132, v132, v189
	v_add_f32_e32 v132, v132, v212
	v_pk_mul_f32 v[214:215], v[18:19], v[18:19]
	v_add_f32_e32 v132, v132, v213
	v_add_f32_e32 v132, v132, v214
	v_pk_mul_f32 v[216:217], v[20:21], v[20:21]
	v_add_f32_e32 v132, v132, v215
	v_add_f32_e32 v132, v132, v216
	v_pk_mul_f32 v[218:219], v[22:23], v[22:23]
	v_add_f32_e32 v132, v132, v217
	v_add_f32_e32 v132, v132, v218
	v_pk_mul_f32 v[220:221], v[24:25], v[24:25]
	v_add_f32_e32 v132, v132, v219
	v_add_f32_e32 v132, v132, v220
	v_pk_mul_f32 v[222:223], v[26:27], v[26:27]
	v_add_f32_e32 v132, v132, v221
	v_add_f32_e32 v132, v132, v222
	v_pk_mul_f32 v[224:225], v[28:29], v[28:29]
	v_add_f32_e32 v132, v132, v223
	v_add_f32_e32 v132, v132, v224
	v_pk_mul_f32 v[226:227], v[30:31], v[30:31]
	v_add_f32_e32 v132, v132, v225
	v_add_f32_e32 v132, v132, v226
	v_pk_mul_f32 v[228:229], v[32:33], v[32:33]
	v_add_f32_e32 v132, v132, v227
	v_add_f32_e32 v132, v132, v228
	v_pk_mul_f32 v[238:239], v[2:3], v[2:3]
	v_add_f32_e32 v132, v132, v229
	v_add_f32_e32 v132, v132, v238
	v_pk_mul_f32 v[240:241], v[4:5], v[4:5]
	v_add_f32_e32 v132, v132, v239
	v_add_f32_e32 v132, v132, v240
	v_pk_mul_f32 v[242:243], v[6:7], v[6:7]
	v_add_f32_e32 v132, v132, v241
	v_add_f32_e32 v132, v132, v242
	v_pk_mul_f32 v[244:245], v[8:9], v[8:9]
	v_add_f32_e32 v132, v132, v243
	v_add_f32_e32 v132, v132, v244
	v_pk_mul_f32 v[230:231], v[10:11], v[10:11]
	v_add_f32_e32 v132, v132, v245
	v_add_f32_e32 v132, v132, v230
	v_pk_mul_f32 v[232:233], v[12:13], v[12:13]
	v_add_f32_e32 v132, v132, v231
	v_add_f32_e32 v132, v132, v232
	v_pk_mul_f32 v[234:235], v[14:15], v[14:15]
	v_add_f32_e32 v132, v132, v233
	v_add_f32_e32 v132, v132, v234
	v_pk_mul_f32 v[236:237], v[16:17], v[16:17]
	v_add_f32_e32 v132, v132, v235
	v_add_f32_e32 v132, v132, v236
	v_add_f32_e32 v151, v132, v237
	ds_bpermute_b32 v147, v147, v151
	v_lshlrev_b32_e32 v132, 1, v141
	v_lshl_add_u64 v[160:161], s[80:81], 0, v[132:133]
	v_lshl_add_u64 v[158:159], v[158:159], 1, v[160:161]
	v_lshl_add_u64 v[158:159], v[158:159], 0, v[152:153]
	s_waitcnt lgkmcnt(0)
	v_add_f32_e32 v132, v151, v147
	v_fmamk_f32 v132, v132, 0x3c000000, v135
	v_mul_f32_e32 v141, 0x4b800000, v132
	v_cmp_gt_f32_e32 vcc, s11, v132
	s_nop 1
	v_cndmask_b32_e32 v132, v132, v141, vcc
	v_rsq_f32_e32 v132, v132
	s_nop 0
	v_mul_f32_e32 v141, 0x45800000, v132
	v_cndmask_b32_e32 v132, v132, v141, vcc
	v_mul_f32_e32 v132, 0x3f4ccccd, v132
	v_pk_mul_f32 v[50:51], v[50:51], v[132:133] op_sel_hi:[1,0]
	v_pk_mul_f32 v[52:53], v[52:53], v[132:133] op_sel_hi:[1,0]
	v_pk_mul_f32 v[34:35], v[34:35], v[132:133] op_sel_hi:[1,0]
	v_pk_mul_f32 v[36:37], v[36:37], v[132:133] op_sel_hi:[1,0]
	v_pk_mul_f32 v[18:19], v[18:19], v[132:133] op_sel_hi:[1,0]
	v_pk_mul_f32 v[20:21], v[20:21], v[132:133] op_sel_hi:[1,0]
	v_pk_mul_f32 v[2:3], v[2:3], v[132:133] op_sel_hi:[1,0]
	v_pk_mul_f32 v[4:5], v[4:5], v[132:133] op_sel_hi:[1,0]
	v_pk_mul_f32 v[50:51], v[66:67], v[50:51]
	v_pk_mul_f32 v[52:53], v[68:69], v[52:53]
	v_pk_mul_f32 v[34:35], v[82:83], v[34:35]
	v_pk_mul_f32 v[36:37], v[84:85], v[36:37]
	v_pk_mul_f32 v[18:19], v[98:99], v[18:19]
	v_pk_mul_f32 v[20:21], v[100:101], v[20:21]
	v_pk_mul_f32 v[2:3], v[114:115], v[2:3]
	v_pk_mul_f32 v[4:5], v[116:117], v[4:5]
	v_mbcnt_lo_u32_b32 v230, -1, 0
	v_mbcnt_hi_u32_b32 v230, -1, v230
	v_and_b32_e32 v230, 32, v230
	v_lshrrev_b32_e32 v230, 2, v230
	v_mov_b32_e32 v231, 0
	v_cvt_pk_bf16_f32 v212, v50, v51
	v_cvt_pk_bf16_f32 v213, v52, v53
	v_cvt_pk_bf16_f32 v216, v34, v35
	v_cvt_pk_bf16_f32 v217, v36, v37
	v_cvt_pk_bf16_f32 v220, v18, v19
	v_cvt_pk_bf16_f32 v221, v20, v21
	v_cvt_pk_bf16_f32 v224, v2, v3
	v_cvt_pk_bf16_f32 v225, v4, v5
	v_pk_mul_f32 v[50:51], v[54:55], v[132:133] op_sel_hi:[1,0]
	v_pk_mul_f32 v[52:53], v[56:57], v[132:133] op_sel_hi:[1,0]
	v_pk_mul_f32 v[34:35], v[38:39], v[132:133] op_sel_hi:[1,0]
	v_pk_mul_f32 v[36:37], v[40:41], v[132:133] op_sel_hi:[1,0]
	v_pk_mul_f32 v[18:19], v[22:23], v[132:133] op_sel_hi:[1,0]
	v_pk_mul_f32 v[20:21], v[24:25], v[132:133] op_sel_hi:[1,0]
	v_pk_mul_f32 v[2:3], v[6:7], v[132:133] op_sel_hi:[1,0]
	v_pk_mul_f32 v[4:5], v[8:9], v[132:133] op_sel_hi:[1,0]
	v_pk_mul_f32 v[50:51], v[70:71], v[50:51]
	v_pk_mul_f32 v[52:53], v[72:73], v[52:53]
	v_pk_mul_f32 v[34:35], v[86:87], v[34:35]
	v_pk_mul_f32 v[36:37], v[88:89], v[36:37]
	v_pk_mul_f32 v[18:19], v[102:103], v[18:19]
	v_pk_mul_f32 v[20:21], v[104:105], v[20:21]
	v_pk_mul_f32 v[2:3], v[118:119], v[2:3]
	v_pk_mul_f32 v[4:5], v[120:121], v[4:5]
	v_cvt_pk_bf16_f32 v214, v50, v51
	v_cvt_pk_bf16_f32 v215, v52, v53
	v_cvt_pk_bf16_f32 v218, v34, v35
	v_cvt_pk_bf16_f32 v219, v36, v37
	v_cvt_pk_bf16_f32 v222, v18, v19
	v_cvt_pk_bf16_f32 v223, v20, v21
	v_cvt_pk_bf16_f32 v226, v2, v3
	v_cvt_pk_bf16_f32 v227, v4, v5
	v_pk_mul_f32 v[50:51], v[58:59], v[132:133] op_sel_hi:[1,0]
	v_pk_mul_f32 v[52:53], v[60:61], v[132:133] op_sel_hi:[1,0]
	v_pk_mul_f32 v[34:35], v[42:43], v[132:133] op_sel_hi:[1,0]
	v_pk_mul_f32 v[36:37], v[44:45], v[132:133] op_sel_hi:[1,0]
	v_pk_mul_f32 v[18:19], v[26:27], v[132:133] op_sel_hi:[1,0]
	v_pk_mul_f32 v[20:21], v[28:29], v[132:133] op_sel_hi:[1,0]
	s_nop 1
	v_permlane32_swap_b32_e32 v212, v214
	v_permlane32_swap_b32_e32 v213, v215
	v_permlane32_swap_b32_e32 v216, v218
	v_permlane32_swap_b32_e32 v217, v219
	v_permlane32_swap_b32_e32 v220, v222
	v_permlane32_swap_b32_e32 v221, v223
	v_permlane32_swap_b32_e32 v224, v226
	v_permlane32_swap_b32_e32 v225, v227
	v_lshl_add_u64 v[228:229], v[158:159], 0, v[230:231]
	global_store_dwordx4 v[228:229], v[212:215], off
	global_store_dwordx4 v[228:229], v[216:219], off offset:64
	global_store_dwordx4 v[228:229], v[220:223], off offset:128
	global_store_dwordx4 v[228:229], v[224:227], off offset:192
	v_pk_mul_f32 v[2:3], v[10:11], v[132:133] op_sel_hi:[1,0]
	v_pk_mul_f32 v[4:5], v[12:13], v[132:133] op_sel_hi:[1,0]
	v_pk_mul_f32 v[50:51], v[74:75], v[50:51]
	v_pk_mul_f32 v[52:53], v[76:77], v[52:53]
	v_pk_mul_f32 v[34:35], v[90:91], v[34:35]
	v_pk_mul_f32 v[36:37], v[92:93], v[36:37]
	v_pk_mul_f32 v[18:19], v[106:107], v[18:19]
	v_pk_mul_f32 v[20:21], v[108:109], v[20:21]
	v_pk_mul_f32 v[2:3], v[122:123], v[2:3]
	v_pk_mul_f32 v[4:5], v[124:125], v[4:5]
	v_cvt_pk_bf16_f32 v212, v50, v51
	v_cvt_pk_bf16_f32 v213, v52, v53
	v_cvt_pk_bf16_f32 v216, v34, v35
	v_cvt_pk_bf16_f32 v217, v36, v37
	v_cvt_pk_bf16_f32 v220, v18, v19
	v_cvt_pk_bf16_f32 v221, v20, v21
	v_cvt_pk_bf16_f32 v224, v2, v3
	v_cvt_pk_bf16_f32 v225, v4, v5
	v_pk_mul_f32 v[50:51], v[62:63], v[132:133] op_sel_hi:[1,0]
	v_pk_mul_f32 v[52:53], v[64:65], v[132:133] op_sel_hi:[1,0]
	v_pk_mul_f32 v[34:35], v[46:47], v[132:133] op_sel_hi:[1,0]
	v_pk_mul_f32 v[36:37], v[48:49], v[132:133] op_sel_hi:[1,0]
	v_pk_mul_f32 v[18:19], v[30:31], v[132:133] op_sel_hi:[1,0]
	v_pk_mul_f32 v[20:21], v[32:33], v[132:133] op_sel_hi:[1,0]
	v_pk_mul_f32 v[2:3], v[14:15], v[132:133] op_sel_hi:[1,0]
	v_pk_mul_f32 v[4:5], v[16:17], v[132:133] op_sel_hi:[1,0]
	v_pk_mul_f32 v[50:51], v[78:79], v[50:51]
	v_pk_mul_f32 v[52:53], v[80:81], v[52:53]
	v_pk_mul_f32 v[34:35], v[94:95], v[34:35]
	v_pk_mul_f32 v[36:37], v[96:97], v[36:37]
	v_pk_mul_f32 v[18:19], v[110:111], v[18:19]
	v_pk_mul_f32 v[20:21], v[112:113], v[20:21]
	v_pk_mul_f32 v[2:3], v[126:127], v[2:3]
	v_pk_mul_f32 v[4:5], v[128:129], v[4:5]
	v_cvt_pk_bf16_f32 v214, v50, v51
	v_cvt_pk_bf16_f32 v215, v52, v53
	v_cvt_pk_bf16_f32 v218, v34, v35
	v_cvt_pk_bf16_f32 v219, v36, v37
	v_cvt_pk_bf16_f32 v222, v18, v19
	v_cvt_pk_bf16_f32 v223, v20, v21
	v_cvt_pk_bf16_f32 v226, v2, v3
	v_cvt_pk_bf16_f32 v227, v4, v5
	s_nop 1
	v_permlane32_swap_b32_e32 v212, v214
	v_permlane32_swap_b32_e32 v213, v215
	v_permlane32_swap_b32_e32 v216, v218
	v_permlane32_swap_b32_e32 v217, v219
	v_permlane32_swap_b32_e32 v220, v222
	v_permlane32_swap_b32_e32 v221, v223
	v_permlane32_swap_b32_e32 v224, v226
	v_permlane32_swap_b32_e32 v225, v227
	v_lshl_add_u64 v[228:229], v[158:159], 0, v[230:231]
	global_store_dwordx4 v[228:229], v[212:215], off offset:32
	global_store_dwordx4 v[228:229], v[216:219], off offset:96
	global_store_dwordx4 v[228:229], v[220:223], off offset:160
	global_store_dwordx4 v[228:229], v[224:227], off offset:224
	s_branch .LBB0_214
